# swa K/V staging: all ten 16-byte loads of a thread issued before one wait (was five serial round trips per item); bias load hoisted
# speedup vs baseline: 1.0125x; 1.0027x over previous
; #define LAS __attribute__((address_space(3)))
; __device__ __forceinline__ unsigned pk2(float lo, float hi) { f32x2c v = {lo, hi}; return __builtin_bit_cast(unsigned, __builtin_convertvector(v, bf16x2c)); }
; __device__ __forceinline__ unsigned short bf1(float f) { return (unsigned short)(pk2(f, 0.f) & 0xffffu); }
; __device__ __forceinline__ void swa_phase(const Params& p, LAS unsigned char* lds8, const int e) {
;     ...
;         __syncthreads();
;         for (int idx = tid; idx < KROWS * 16; idx += 512) {
;             const int r = idx >> 4, c = (idx & 15) * 4;
;             f32x4 kv = (f32x4){0.f, 0.f, 0.f, 0.f}, vv = kv;
;             if (!samp) { const int pos = q0 - 127 + r; if (pos >= 0 && r < 159) { const float* src = PROJ + (size_t)(b * SEQ + pos) * IN_EVEN + 5120 + kh * 64 + c; kv = *(const f32x4*)src; vv = *(const f32x4*)(src + 256); } }
;             else if (r < 128) { const size_t o_ = ((size_t)b * 128 + r) * 256 + kh * 64 + c; kv = *(const f32x4*)(cK + o_); vv = *(const f32x4*)(cV + o_); }
;             else if (r < 136) { const float* src = PROJ + (size_t)(MP + b * DSEQ + r - 128) * IN_EVEN + 5120 + kh * 64 + c; kv = *(const f32x4*)src; vv = *(const f32x4*)(src + 256); }
;             u32x2 kw; kw.x = pk2(kv[0], kv[1]); kw.y = pk2(kv[2], kv[3]); *(LAS u32x2*)(Kb + r * SW_KS + c) = kw;
;             VTb[(c + 0) * SW_VS + r] = bf1(vv[0]); VTb[(c + 1) * SW_VS + r] = bf1(vv[1]); VTb[(c + 2) * SW_VS + r] = bf1(vv[2]); VTb[(c + 3) * SW_VS + r] = bf1(vv[3]);
;         }
;         { const int d = tid >> 2, hh = tid & 3; int bkt = d;
;           if (d >= 16) { bkt = 16 + (int)(logf((float)d * 0.0625f) * (16.0f / 2.0794415416798357f)); bkt = bkt > 31 ? 31 : bkt; }
;           biasT[tid] = IN(15)[bkt * 16 + kh * 4 + hh]; }
.LBB0_1133:
	s_and_b32 s54, s12, 3
	s_barrier
	s_movk_i32 s12, 0x78
	s_ashr_i32 s13, s12, 31
	s_add_u32 s12, s0, s12
	s_addc_u32 s13, s1, s13
	s_load_dwordx2 s[12:13], s[12:13], 0x0
	s_lshl_b32 s15, s54, 2
	v_or_b32_e32 v202, s15, v34
	v_ashrrev_i32_e32 v203, 31, v202
	s_waitcnt lgkmcnt(0)
	v_lshl_add_u64 v[202:203], v[202:203], 2, s[12:13]
	global_load_dword v201, v[202:203], off
	s_and_saveexec_b64 s[26:27], s[6:7]
	s_cbranch_execz .LBB0_1148
	s_ashr_i32 s15, s14, 31
	s_lshl_b32 s55, s14, 3
	s_lshl_b32 s61, s54, 6
	s_lshl_b64 s[30:31], s[14:15], 15
	s_addk_i32 s55, 0x1f80
	s_or_b32 s30, s30, s61
	s_add_i32 s15, s39, 0xffffff81
	s_lshl_b32 s66, s14, 12
	v_and_b32_e32 v14, 60, v21
	v_ashrrev_i32_e32 v200, 4, v26
	s_and_b64 vcc, exec, s[24:25]
	s_cbranch_vccz .Lsw_prompt
	v_add_u32_e32 v0, 0, v200
	v_mov_b32_e32 v163, 0
	v_mov_b32_e32 v162, 0
	v_mov_b32_e32 v161, 0
	v_mov_b32_e32 v160, 0
	v_mov_b32_e32 v167, 0
	v_mov_b32_e32 v166, 0
	v_mov_b32_e32 v165, 0
	v_mov_b32_e32 v164, 0
	v_cmp_lt_i32_e32 vcc, s44, v0
	s_and_saveexec_b64 s[12:13], vcc
	s_xor_b64 s[12:13], exec, s[12:13]
	s_cbranch_execz .Lsw_s0_c
	s_movk_i32 s46, 0x88
	v_cmp_gt_u32_e32 vcc, s46, v0
	s_and_saveexec_b64 s[46:47], vcc
	s_cbranch_execz .Lsw_s0_b
	v_add_u32_e32 v1, s55, v0
	v_mov_b64_e32 v[160:161], s[2:3]
	v_mad_i64_i32 v[160:161], s[70:71], v1, s33, v[160:161]
	s_lshl_b32 s52, s61, 2
	v_lshl_add_u64 v[160:161], v[160:161], 0, s[52:53]
	v_lshlrev_b32_e32 v2, 2, v14
	v_lshl_add_u64 v[160:161], v[160:161], 0, v[2:3]
	v_lshl_add_u64 v[164:165], v[160:161], 0, s[58:59]
	v_add_co_u32_e32 v160, vcc, 0x5000, v160
	s_nop 1
	v_addc_co_u32_e32 v161, vcc, 0, v161, vcc
	global_load_dwordx4 v[160:163], v[160:161], off
	s_nop 0
	global_load_dwordx4 v[164:167], v[164:165], off offset:1024

; __device__ __forceinline__ void swa_phase(const Params& p, LAS unsigned char* lds8, const int e) {
;     ...
;         for (int idx = tid; idx < KROWS * 16; idx += 512) {
;             const int r = idx >> 4, c = (idx & 15) * 4;
;             f32x4 kv = (f32x4){0.f, 0.f, 0.f, 0.f}, vv = kv;
;             if (!samp) { const int pos = q0 - 127 + r; if (pos >= 0 && r < 159) { const float* src = PROJ + (size_t)(b * SEQ + pos) * IN_EVEN + 5120 + kh * 64 + c; kv = *(const f32x4*)src; vv = *(const f32x4*)(src + 256); } }
;             else if (r < 128) { const size_t o_ = ((size_t)b * 128 + r) * 256 + kh * 64 + c; kv = *(const f32x4*)(cK + o_); vv = *(const f32x4*)(cV + o_); }
;             else if (r < 136) { const float* src = PROJ + (size_t)(MP + b * DSEQ + r - 128) * IN_EVEN + 5120 + kh * 64 + c; kv = *(const f32x4*)src; vv = *(const f32x4*)(src + 256); }
.Lsw_s0_c:
	s_andn2_saveexec_b64 s[12:13], s[12:13]
	s_cbranch_execz .Lsw_s0_d
	v_ashrrev_i32_e32 v1, 31, v0
	v_lshlrev_b64 v[160:161], 8, v[0:1]
	v_lshl_add_u64 v[160:161], s[30:31], 0, v[160:161]
	v_or_b32_e32 v160, v160, v14
	v_lshlrev_b64 v[164:165], 2, v[160:161]
	v_lshl_add_u64 v[160:161], s[16:17], 0, v[164:165]
	v_lshl_add_u64 v[164:165], s[18:19], 0, v[164:165]
	global_load_dwordx4 v[160:163], v[160:161], off
	s_nop 0
	global_load_dwordx4 v[164:167], v[164:165], off
.Lsw_s0_d:
	s_or_b64 exec, exec, s[12:13]
	v_add_u32_e32 v0, 32, v200
	v_mov_b32_e32 v171, 0
	v_mov_b32_e32 v170, 0
	v_mov_b32_e32 v169, 0
	v_mov_b32_e32 v168, 0
	v_mov_b32_e32 v175, 0
	v_mov_b32_e32 v174, 0
	v_mov_b32_e32 v173, 0
	v_mov_b32_e32 v172, 0
	v_cmp_lt_i32_e32 vcc, s44, v0
	s_and_saveexec_b64 s[12:13], vcc
	s_xor_b64 s[12:13], exec, s[12:13]
	s_cbranch_execz .Lsw_s1_c
	s_movk_i32 s46, 0x88
	v_cmp_gt_u32_e32 vcc, s46, v0
	s_and_saveexec_b64 s[46:47], vcc
	s_cbranch_execz .Lsw_s1_b
	v_add_u32_e32 v1, s55, v0
	v_mov_b64_e32 v[168:169], s[2:3]
	v_mad_i64_i32 v[168:169], s[70:71], v1, s33, v[168:169]
	s_lshl_b32 s52, s61, 2
	v_lshl_add_u64 v[168:169], v[168:169], 0, s[52:53]
	v_lshlrev_b32_e32 v2, 2, v14
	v_lshl_add_u64 v[168:169], v[168:169], 0, v[2:3]
	v_lshl_add_u64 v[172:173], v[168:169], 0, s[58:59]
	v_add_co_u32_e32 v168, vcc, 0x5000, v168
	s_nop 1
	v_addc_co_u32_e32 v169, vcc, 0, v169, vcc
	global_load_dwordx4 v[168:171], v[168:169], off
	s_nop 0
	global_load_dwordx4 v[172:175], v[172:173], off offset:1024

; __device__ __forceinline__ void swa_phase(const Params& p, LAS unsigned char* lds8, const int e) {
;     ...
;         for (int idx = tid; idx < KROWS * 16; idx += 512) {
;             const int r = idx >> 4, c = (idx & 15) * 4;
;             f32x4 kv = (f32x4){0.f, 0.f, 0.f, 0.f}, vv = kv;
;             if (!samp) { const int pos = q0 - 127 + r; if (pos >= 0 && r < 159) { const float* src = PROJ + (size_t)(b * SEQ + pos) * IN_EVEN + 5120 + kh * 64 + c; kv = *(const f32x4*)src; vv = *(const f32x4*)(src + 256); } }
;             else if (r < 128) { const size_t o_ = ((size_t)b * 128 + r) * 256 + kh * 64 + c; kv = *(const f32x4*)(cK + o_); vv = *(const f32x4*)(cV + o_); }
;             else if (r < 136) { const float* src = PROJ + (size_t)(MP + b * DSEQ + r - 128) * IN_EVEN + 5120 + kh * 64 + c; kv = *(const f32x4*)src; vv = *(const f32x4*)(src + 256); }
.Lsw_s1_c:
	s_andn2_saveexec_b64 s[12:13], s[12:13]
	s_cbranch_execz .Lsw_s1_d
	v_ashrrev_i32_e32 v1, 31, v0
	v_lshlrev_b64 v[168:169], 8, v[0:1]
	v_lshl_add_u64 v[168:169], s[30:31], 0, v[168:169]
	v_or_b32_e32 v168, v168, v14
	v_lshlrev_b64 v[172:173], 2, v[168:169]
	v_lshl_add_u64 v[168:169], s[16:17], 0, v[172:173]
	v_lshl_add_u64 v[172:173], s[18:19], 0, v[172:173]
	global_load_dwordx4 v[168:171], v[168:169], off
	s_nop 0
	global_load_dwordx4 v[172:175], v[172:173], off
.Lsw_s1_d:
	s_or_b64 exec, exec, s[12:13]
	v_add_u32_e32 v0, 64, v200
	v_mov_b32_e32 v179, 0
	v_mov_b32_e32 v178, 0
	v_mov_b32_e32 v177, 0
	v_mov_b32_e32 v176, 0
	v_mov_b32_e32 v183, 0
	v_mov_b32_e32 v182, 0
	v_mov_b32_e32 v181, 0
	v_mov_b32_e32 v180, 0
	v_cmp_lt_i32_e32 vcc, s44, v0
	s_and_saveexec_b64 s[12:13], vcc
	s_xor_b64 s[12:13], exec, s[12:13]
	s_cbranch_execz .Lsw_s2_c
	s_movk_i32 s46, 0x88
	v_cmp_gt_u32_e32 vcc, s46, v0
	s_and_saveexec_b64 s[46:47], vcc
	s_cbranch_execz .Lsw_s2_b
	v_add_u32_e32 v1, s55, v0
	v_mov_b64_e32 v[176:177], s[2:3]
	v_mad_i64_i32 v[176:177], s[70:71], v1, s33, v[176:177]
	s_lshl_b32 s52, s61, 2
	v_lshl_add_u64 v[176:177], v[176:177], 0, s[52:53]
	v_lshlrev_b32_e32 v2, 2, v14
	v_lshl_add_u64 v[176:177], v[176:177], 0, v[2:3]
	v_lshl_add_u64 v[180:181], v[176:177], 0, s[58:59]
	v_add_co_u32_e32 v176, vcc, 0x5000, v176
	s_nop 1
	v_addc_co_u32_e32 v177, vcc, 0, v177, vcc
	global_load_dwordx4 v[176:179], v[176:177], off
	s_nop 0
	global_load_dwordx4 v[180:183], v[180:181], off offset:1024

; __device__ __forceinline__ void swa_phase(const Params& p, LAS unsigned char* lds8, const int e) {
;     ...
;         for (int idx = tid; idx < KROWS * 16; idx += 512) {
;             const int r = idx >> 4, c = (idx & 15) * 4;
;             f32x4 kv = (f32x4){0.f, 0.f, 0.f, 0.f}, vv = kv;
;             if (!samp) { const int pos = q0 - 127 + r; if (pos >= 0 && r < 159) { const float* src = PROJ + (size_t)(b * SEQ + pos) * IN_EVEN + 5120 + kh * 64 + c; kv = *(const f32x4*)src; vv = *(const f32x4*)(src + 256); } }
;             else if (r < 128) { const size_t o_ = ((size_t)b * 128 + r) * 256 + kh * 64 + c; kv = *(const f32x4*)(cK + o_); vv = *(const f32x4*)(cV + o_); }
;             else if (r < 136) { const float* src = PROJ + (size_t)(MP + b * DSEQ + r - 128) * IN_EVEN + 5120 + kh * 64 + c; kv = *(const f32x4*)src; vv = *(const f32x4*)(src + 256); }
.Lsw_s2_c:
	s_andn2_saveexec_b64 s[12:13], s[12:13]
	s_cbranch_execz .Lsw_s2_d
	v_ashrrev_i32_e32 v1, 31, v0
	v_lshlrev_b64 v[176:177], 8, v[0:1]
	v_lshl_add_u64 v[176:177], s[30:31], 0, v[176:177]
	v_or_b32_e32 v176, v176, v14
	v_lshlrev_b64 v[180:181], 2, v[176:177]
	v_lshl_add_u64 v[176:177], s[16:17], 0, v[180:181]
	v_lshl_add_u64 v[180:181], s[18:19], 0, v[180:181]
	global_load_dwordx4 v[176:179], v[176:177], off
	s_nop 0
	global_load_dwordx4 v[180:183], v[180:181], off
.Lsw_s2_d:
	s_or_b64 exec, exec, s[12:13]
	v_add_u32_e32 v0, 96, v200
	v_mov_b32_e32 v187, 0
	v_mov_b32_e32 v186, 0
	v_mov_b32_e32 v185, 0
	v_mov_b32_e32 v184, 0
	v_mov_b32_e32 v191, 0
	v_mov_b32_e32 v190, 0
	v_mov_b32_e32 v189, 0
	v_mov_b32_e32 v188, 0
	v_cmp_lt_i32_e32 vcc, s44, v0
	s_and_saveexec_b64 s[12:13], vcc
	s_xor_b64 s[12:13], exec, s[12:13]
	s_cbranch_execz .Lsw_s3_c
	s_movk_i32 s46, 0x88
	v_cmp_gt_u32_e32 vcc, s46, v0
	s_and_saveexec_b64 s[46:47], vcc
	s_cbranch_execz .Lsw_s3_b
	v_add_u32_e32 v1, s55, v0
	v_mov_b64_e32 v[184:185], s[2:3]
	v_mad_i64_i32 v[184:185], s[70:71], v1, s33, v[184:185]
	s_lshl_b32 s52, s61, 2
	v_lshl_add_u64 v[184:185], v[184:185], 0, s[52:53]
	v_lshlrev_b32_e32 v2, 2, v14
	v_lshl_add_u64 v[184:185], v[184:185], 0, v[2:3]
	v_lshl_add_u64 v[188:189], v[184:185], 0, s[58:59]
	v_add_co_u32_e32 v184, vcc, 0x5000, v184
	s_nop 1
	v_addc_co_u32_e32 v185, vcc, 0, v185, vcc
	global_load_dwordx4 v[184:187], v[184:185], off
	s_nop 0
	global_load_dwordx4 v[188:191], v[188:189], off offset:1024

; __device__ __forceinline__ void swa_phase(const Params& p, LAS unsigned char* lds8, const int e) {
;     ...
;         for (int idx = tid; idx < KROWS * 16; idx += 512) {
;             const int r = idx >> 4, c = (idx & 15) * 4;
;             f32x4 kv = (f32x4){0.f, 0.f, 0.f, 0.f}, vv = kv;
;             if (!samp) { const int pos = q0 - 127 + r; if (pos >= 0 && r < 159) { const float* src = PROJ + (size_t)(b * SEQ + pos) * IN_EVEN + 5120 + kh * 64 + c; kv = *(const f32x4*)src; vv = *(const f32x4*)(src + 256); } }
;             else if (r < 128) { const size_t o_ = ((size_t)b * 128 + r) * 256 + kh * 64 + c; kv = *(const f32x4*)(cK + o_); vv = *(const f32x4*)(cV + o_); }
;             else if (r < 136) { const float* src = PROJ + (size_t)(MP + b * DSEQ + r - 128) * IN_EVEN + 5120 + kh * 64 + c; kv = *(const f32x4*)src; vv = *(const f32x4*)(src + 256); }
.Lsw_s3_c:
	s_andn2_saveexec_b64 s[12:13], s[12:13]
	s_cbranch_execz .Lsw_s3_d
	v_ashrrev_i32_e32 v1, 31, v0
	v_lshlrev_b64 v[184:185], 8, v[0:1]
	v_lshl_add_u64 v[184:185], s[30:31], 0, v[184:185]
	v_or_b32_e32 v184, v184, v14
	v_lshlrev_b64 v[188:189], 2, v[184:185]
	v_lshl_add_u64 v[184:185], s[16:17], 0, v[188:189]
	v_lshl_add_u64 v[188:189], s[18:19], 0, v[188:189]
	global_load_dwordx4 v[184:187], v[184:185], off
	s_nop 0
	global_load_dwordx4 v[188:191], v[188:189], off
.Lsw_s3_d:
	s_or_b64 exec, exec, s[12:13]
	v_add_u32_e32 v0, 128, v200
	v_mov_b32_e32 v195, 0
	v_mov_b32_e32 v194, 0
	v_mov_b32_e32 v193, 0
	v_mov_b32_e32 v192, 0
	v_mov_b32_e32 v199, 0
	v_mov_b32_e32 v198, 0
	v_mov_b32_e32 v197, 0
	v_mov_b32_e32 v196, 0
	v_cmp_lt_i32_e32 vcc, s44, v0
	s_and_saveexec_b64 s[12:13], vcc
	s_xor_b64 s[12:13], exec, s[12:13]
	s_cbranch_execz .Lsw_s4_c
	s_movk_i32 s46, 0x88
	v_cmp_gt_u32_e32 vcc, s46, v0
	s_and_saveexec_b64 s[46:47], vcc
	s_cbranch_execz .Lsw_s4_b
	v_add_u32_e32 v1, s55, v0
	v_mov_b64_e32 v[192:193], s[2:3]
	v_mad_i64_i32 v[192:193], s[70:71], v1, s33, v[192:193]
	s_lshl_b32 s52, s61, 2
	v_lshl_add_u64 v[192:193], v[192:193], 0, s[52:53]
	v_lshlrev_b32_e32 v2, 2, v14
	v_lshl_add_u64 v[192:193], v[192:193], 0, v[2:3]
	v_lshl_add_u64 v[196:197], v[192:193], 0, s[58:59]
	v_add_co_u32_e32 v192, vcc, 0x5000, v192
	s_nop 1
	v_addc_co_u32_e32 v193, vcc, 0, v193, vcc
	global_load_dwordx4 v[192:195], v[192:193], off
	s_nop 0
	global_load_dwordx4 v[196:199], v[196:197], off offset:1024

; __device__ __forceinline__ void swa_phase(const Params& p, LAS unsigned char* lds8, const int e) {
;     ...
;         for (int idx = tid; idx < KROWS * 16; idx += 512) {
;             const int r = idx >> 4, c = (idx & 15) * 4;
;             f32x4 kv = (f32x4){0.f, 0.f, 0.f, 0.f}, vv = kv;
;             if (!samp) { const int pos = q0 - 127 + r; if (pos >= 0 && r < 159) { const float* src = PROJ + (size_t)(b * SEQ + pos) * IN_EVEN + 5120 + kh * 64 + c; kv = *(const f32x4*)src; vv = *(const f32x4*)(src + 256); } }
;             else if (r < 128) { const size_t o_ = ((size_t)b * 128 + r) * 256 + kh * 64 + c; kv = *(const f32x4*)(cK + o_); vv = *(const f32x4*)(cV + o_); }
;             else if (r < 136) { const float* src = PROJ + (size_t)(MP + b * DSEQ + r - 128) * IN_EVEN + 5120 + kh * 64 + c; kv = *(const f32x4*)src; vv = *(const f32x4*)(src + 256); }
.Lsw_s4_c:
	s_andn2_saveexec_b64 s[12:13], s[12:13]
	s_cbranch_execz .Lsw_s4_d
	v_ashrrev_i32_e32 v1, 31, v0
	v_lshlrev_b64 v[192:193], 8, v[0:1]
	v_lshl_add_u64 v[192:193], s[30:31], 0, v[192:193]
	v_or_b32_e32 v192, v192, v14
	v_lshlrev_b64 v[196:197], 2, v[192:193]
	v_lshl_add_u64 v[192:193], s[16:17], 0, v[196:197]
	v_lshl_add_u64 v[196:197], s[18:19], 0, v[196:197]
	global_load_dwordx4 v[192:195], v[192:193], off
	s_nop 0
	global_load_dwordx4 v[196:199], v[196:197], off
.Lsw_s4_d:
	s_or_b64 exec, exec, s[12:13]
	s_branch .Lsw_write
.Lsw_prompt:
	v_add_u32_e32 v0, 0, v200
	v_add_u32_e32 v1, s15, v0
	s_movk_i32 s12, 0x9f
	v_cmp_lt_i32_e32 vcc, -1, v1
	v_cmp_gt_i32_e64 s[12:13], s12, v0
	s_and_b64 s[46:47], s[12:13], vcc
	v_mov_b32_e32 v163, 0
	v_mov_b32_e32 v162, 0
	v_mov_b32_e32 v161, 0
	v_mov_b32_e32 v160, 0
	v_mov_b32_e32 v167, 0
	v_mov_b32_e32 v166, 0
	v_mov_b32_e32 v165, 0
	v_mov_b32_e32 v164, 0
	s_and_saveexec_b64 s[12:13], s[46:47]
	s_cbranch_execz .Lsw_p0
	v_add_u32_e32 v1, s66, v1
	v_mov_b64_e32 v[160:161], s[2:3]
	v_mad_i64_i32 v[160:161], s[46:47], v1, s33, v[160:161]
	s_lshl_b32 s52, s61, 2
	v_lshl_add_u64 v[160:161], v[160:161], 0, s[52:53]
	v_lshlrev_b32_e32 v2, 2, v14
	v_lshl_add_u64 v[160:161], v[160:161], 0, v[2:3]
	v_lshl_add_u64 v[164:165], v[160:161], 0, s[58:59]
	v_add_co_u32_e32 v160, vcc, 0x5000, v160
	s_nop 1
	v_addc_co_u32_e32 v161, vcc, 0, v161, vcc
	global_load_dwordx4 v[160:163], v[160:161], off
	s_nop 0
	global_load_dwordx4 v[164:167], v[164:165], off offset:1024
.Lsw_p0:
	s_or_b64 exec, exec, s[12:13]
	v_add_u32_e32 v0, 32, v200
	v_add_u32_e32 v1, s15, v0
	s_movk_i32 s12, 0x9f
	v_cmp_lt_i32_e32 vcc, -1, v1
	v_cmp_gt_i32_e64 s[12:13], s12, v0
	s_and_b64 s[46:47], s[12:13], vcc
	v_mov_b32_e32 v171, 0
	v_mov_b32_e32 v170, 0
	v_mov_b32_e32 v169, 0
	v_mov_b32_e32 v168, 0
	v_mov_b32_e32 v175, 0
	v_mov_b32_e32 v174, 0
	v_mov_b32_e32 v173, 0
	v_mov_b32_e32 v172, 0
	s_and_saveexec_b64 s[12:13], s[46:47]
	s_cbranch_execz .Lsw_p1
	v_add_u32_e32 v1, s66, v1
	v_mov_b64_e32 v[168:169], s[2:3]
	v_mad_i64_i32 v[168:169], s[46:47], v1, s33, v[168:169]
	s_lshl_b32 s52, s61, 2
	v_lshl_add_u64 v[168:169], v[168:169], 0, s[52:53]
	v_lshlrev_b32_e32 v2, 2, v14
	v_lshl_add_u64 v[168:169], v[168:169], 0, v[2:3]
	v_lshl_add_u64 v[172:173], v[168:169], 0, s[58:59]
	v_add_co_u32_e32 v168, vcc, 0x5000, v168
	s_nop 1
	v_addc_co_u32_e32 v169, vcc, 0, v169, vcc
	global_load_dwordx4 v[168:171], v[168:169], off
	s_nop 0
	global_load_dwordx4 v[172:175], v[172:173], off offset:1024
.Lsw_p1:
	s_or_b64 exec, exec, s[12:13]
	v_add_u32_e32 v0, 64, v200
	v_add_u32_e32 v1, s15, v0
	s_movk_i32 s12, 0x9f
	v_cmp_lt_i32_e32 vcc, -1, v1
	v_cmp_gt_i32_e64 s[12:13], s12, v0
	s_and_b64 s[46:47], s[12:13], vcc
	v_mov_b32_e32 v179, 0
	v_mov_b32_e32 v178, 0
	v_mov_b32_e32 v177, 0
	v_mov_b32_e32 v176, 0
	v_mov_b32_e32 v183, 0
	v_mov_b32_e32 v182, 0
	v_mov_b32_e32 v181, 0
	v_mov_b32_e32 v180, 0
	s_and_saveexec_b64 s[12:13], s[46:47]
	s_cbranch_execz .Lsw_p2
	v_add_u32_e32 v1, s66, v1
	v_mov_b64_e32 v[176:177], s[2:3]
	v_mad_i64_i32 v[176:177], s[46:47], v1, s33, v[176:177]
	s_lshl_b32 s52, s61, 2
	v_lshl_add_u64 v[176:177], v[176:177], 0, s[52:53]
	v_lshlrev_b32_e32 v2, 2, v14
	v_lshl_add_u64 v[176:177], v[176:177], 0, v[2:3]
	v_lshl_add_u64 v[180:181], v[176:177], 0, s[58:59]
	v_add_co_u32_e32 v176, vcc, 0x5000, v176
	s_nop 1
	v_addc_co_u32_e32 v177, vcc, 0, v177, vcc
	global_load_dwordx4 v[176:179], v[176:177], off
	s_nop 0
	global_load_dwordx4 v[180:183], v[180:181], off offset:1024
.Lsw_p2:
	s_or_b64 exec, exec, s[12:13]
	v_add_u32_e32 v0, 96, v200
	v_add_u32_e32 v1, s15, v0
	s_movk_i32 s12, 0x9f
	v_cmp_lt_i32_e32 vcc, -1, v1
	v_cmp_gt_i32_e64 s[12:13], s12, v0
	s_and_b64 s[46:47], s[12:13], vcc
	v_mov_b32_e32 v187, 0
	v_mov_b32_e32 v186, 0
	v_mov_b32_e32 v185, 0
	v_mov_b32_e32 v184, 0
	v_mov_b32_e32 v191, 0
	v_mov_b32_e32 v190, 0
	v_mov_b32_e32 v189, 0
	v_mov_b32_e32 v188, 0
	s_and_saveexec_b64 s[12:13], s[46:47]
	s_cbranch_execz .Lsw_p3
	v_add_u32_e32 v1, s66, v1
	v_mov_b64_e32 v[184:185], s[2:3]
	v_mad_i64_i32 v[184:185], s[46:47], v1, s33, v[184:185]
	s_lshl_b32 s52, s61, 2
	v_lshl_add_u64 v[184:185], v[184:185], 0, s[52:53]
	v_lshlrev_b32_e32 v2, 2, v14
	v_lshl_add_u64 v[184:185], v[184:185], 0, v[2:3]
	v_lshl_add_u64 v[188:189], v[184:185], 0, s[58:59]
	v_add_co_u32_e32 v184, vcc, 0x5000, v184
	s_nop 1
	v_addc_co_u32_e32 v185, vcc, 0, v185, vcc
	global_load_dwordx4 v[184:187], v[184:185], off
	s_nop 0
	global_load_dwordx4 v[188:191], v[188:189], off offset:1024
.Lsw_p3:
	s_or_b64 exec, exec, s[12:13]
	v_add_u32_e32 v0, 128, v200
	v_add_u32_e32 v1, s15, v0
	s_movk_i32 s12, 0x9f
	v_cmp_lt_i32_e32 vcc, -1, v1
	v_cmp_gt_i32_e64 s[12:13], s12, v0
	s_and_b64 s[46:47], s[12:13], vcc
	v_mov_b32_e32 v195, 0
	v_mov_b32_e32 v194, 0
	v_mov_b32_e32 v193, 0
	v_mov_b32_e32 v192, 0
	v_mov_b32_e32 v199, 0
	v_mov_b32_e32 v198, 0
	v_mov_b32_e32 v197, 0
	v_mov_b32_e32 v196, 0
	s_and_saveexec_b64 s[12:13], s[46:47]
	s_cbranch_execz .Lsw_p4
	v_add_u32_e32 v1, s66, v1
	v_mov_b64_e32 v[192:193], s[2:3]
	v_mad_i64_i32 v[192:193], s[46:47], v1, s33, v[192:193]
	s_lshl_b32 s52, s61, 2
	v_lshl_add_u64 v[192:193], v[192:193], 0, s[52:53]
	v_lshlrev_b32_e32 v2, 2, v14
	v_lshl_add_u64 v[192:193], v[192:193], 0, v[2:3]
	v_lshl_add_u64 v[196:197], v[192:193], 0, s[58:59]
	v_add_co_u32_e32 v192, vcc, 0x5000, v192
	s_nop 1
	v_addc_co_u32_e32 v193, vcc, 0, v193, vcc
	global_load_dwordx4 v[192:195], v[192:193], off
	s_nop 0
	global_load_dwordx4 v[196:199], v[196:197], off offset:1024

; #define LAS __attribute__((address_space(3)))
; __device__ __forceinline__ unsigned pk2(float lo, float hi) { f32x2c v = {lo, hi}; return __builtin_bit_cast(unsigned, __builtin_convertvector(v, bf16x2c)); }
; __device__ __forceinline__ unsigned short bf1(float f) { return (unsigned short)(pk2(f, 0.f) & 0xffffu); }
; __device__ __forceinline__ void swa_phase(const Params& p, LAS unsigned char* lds8, const int e) {
;     ...
;             u32x2 kw; kw.x = pk2(kv[0], kv[1]); kw.y = pk2(kv[2], kv[3]); *(LAS u32x2*)(Kb + r * SW_KS + c) = kw;
;             VTb[(c + 0) * SW_VS + r] = bf1(vv[0]); VTb[(c + 1) * SW_VS + r] = bf1(vv[1]); VTb[(c + 2) * SW_VS + r] = bf1(vv[2]); VTb[(c + 3) * SW_VS + r] = bf1(vv[3]);
;         }
;         { const int d = tid >> 2, hh = tid & 3; int bkt = d;
;           if (d >= 16) { bkt = 16 + (int)(logf((float)d * 0.0625f) * (16.0f / 2.0794415416798357f)); bkt = bkt > 31 ? 31 : bkt; }
;           biasT[tid] = IN(15)[bkt * 16 + kh * 4 + hh]; }
;         __syncthreads();
.Lsw_write:
	s_waitcnt vmcnt(0)
	v_add_u32_e32 v0, 0, v200
	v_mul_lo_u32 v1, v0, s51
	v_lshlrev_b32_e32 v2, 1, v14
	v_cvt_pk_bf16_f32 v160, v160, v161
	v_cvt_pk_bf16_f32 v161, v162, v163
	v_add3_u32 v1, 0, v1, v2
	v_mul_u32_u24_e32 v2, 0x150, v14
	v_lshlrev_b32_e32 v0, 1, v0
	ds_write_b64 v1, v[160:161]
	v_cvt_pk_bf16_f32 v1, v164, s0
	v_add3_u32 v0, 0, v2, v0
	ds_write_b16 v0, v1 offset:23040
	v_cvt_pk_bf16_f32 v1, v165, s0
	ds_write_b16 v0, v1 offset:23376
	v_cvt_pk_bf16_f32 v1, v166, s0
	ds_write_b16 v0, v1 offset:23712
	v_cvt_pk_bf16_f32 v1, v167, s0
	ds_write_b16 v0, v1 offset:24048
	v_add_u32_e32 v0, 32, v200
	v_mul_lo_u32 v1, v0, s51
	v_lshlrev_b32_e32 v2, 1, v14
	v_cvt_pk_bf16_f32 v168, v168, v169
	v_cvt_pk_bf16_f32 v169, v170, v171
	v_add3_u32 v1, 0, v1, v2
	v_mul_u32_u24_e32 v2, 0x150, v14
	v_lshlrev_b32_e32 v0, 1, v0
	ds_write_b64 v1, v[168:169]
	v_cvt_pk_bf16_f32 v1, v172, s0
	v_add3_u32 v0, 0, v2, v0
	ds_write_b16 v0, v1 offset:23040
	v_cvt_pk_bf16_f32 v1, v173, s0
	ds_write_b16 v0, v1 offset:23376
	v_cvt_pk_bf16_f32 v1, v174, s0
	ds_write_b16 v0, v1 offset:23712
	v_cvt_pk_bf16_f32 v1, v175, s0
	ds_write_b16 v0, v1 offset:24048
	v_add_u32_e32 v0, 64, v200
	v_mul_lo_u32 v1, v0, s51
	v_lshlrev_b32_e32 v2, 1, v14
	v_cvt_pk_bf16_f32 v176, v176, v177
	v_cvt_pk_bf16_f32 v177, v178, v179
	v_add3_u32 v1, 0, v1, v2
	v_mul_u32_u24_e32 v2, 0x150, v14
	v_lshlrev_b32_e32 v0, 1, v0
	ds_write_b64 v1, v[176:177]
	v_cvt_pk_bf16_f32 v1, v180, s0
	v_add3_u32 v0, 0, v2, v0
	ds_write_b16 v0, v1 offset:23040
	v_cvt_pk_bf16_f32 v1, v181, s0
	ds_write_b16 v0, v1 offset:23376
	v_cvt_pk_bf16_f32 v1, v182, s0
	ds_write_b16 v0, v1 offset:23712
	v_cvt_pk_bf16_f32 v1, v183, s0
	ds_write_b16 v0, v1 offset:24048
	v_add_u32_e32 v0, 96, v200
	v_mul_lo_u32 v1, v0, s51
	v_lshlrev_b32_e32 v2, 1, v14
	v_cvt_pk_bf16_f32 v184, v184, v185
	v_cvt_pk_bf16_f32 v185, v186, v187
	v_add3_u32 v1, 0, v1, v2
	v_mul_u32_u24_e32 v2, 0x150, v14
	v_lshlrev_b32_e32 v0, 1, v0
	ds_write_b64 v1, v[184:185]
	v_cvt_pk_bf16_f32 v1, v188, s0
	v_add3_u32 v0, 0, v2, v0
	ds_write_b16 v0, v1 offset:23040
	v_cvt_pk_bf16_f32 v1, v189, s0
	ds_write_b16 v0, v1 offset:23376
	v_cvt_pk_bf16_f32 v1, v190, s0
	ds_write_b16 v0, v1 offset:23712
	v_cvt_pk_bf16_f32 v1, v191, s0
	ds_write_b16 v0, v1 offset:24048
	v_add_u32_e32 v0, 128, v200
	v_mul_lo_u32 v1, v0, s51
	v_lshlrev_b32_e32 v2, 1, v14
	v_cvt_pk_bf16_f32 v192, v192, v193
	v_cvt_pk_bf16_f32 v193, v194, v195
	v_add3_u32 v1, 0, v1, v2
	v_mul_u32_u24_e32 v2, 0x150, v14
	v_lshlrev_b32_e32 v0, 1, v0
	ds_write_b64 v1, v[192:193]
	v_cvt_pk_bf16_f32 v1, v196, s0
	v_add3_u32 v0, 0, v2, v0
	ds_write_b16 v0, v1 offset:23040
	v_cvt_pk_bf16_f32 v1, v197, s0
	ds_write_b16 v0, v1 offset:23376
	v_cvt_pk_bf16_f32 v1, v198, s0
	ds_write_b16 v0, v1 offset:23712
	v_cvt_pk_bf16_f32 v1, v199, s0
	ds_write_b16 v0, v1 offset:24048
.LBB0_1148:
	s_or_b64 exec, exec, s[26:27]
	s_lshl_b32 s15, s54, 2
	s_movk_i32 s55, 0x1000
	s_or_b64 s[12:13], s[22:23], s[10:11]
	s_and_b64 vcc, exec, s[12:13]
	s_mov_b32 s61, 0x14f00000
	s_waitcnt vmcnt(0)
	ds_write_b32 v28, v201 offset:44544
	s_waitcnt lgkmcnt(0)
	s_barrier
	s_cbranch_vccz .LBB0_1128
	s_andn2_b64 vcc, exec, s[24:25]
	s_mov_b64 s[12:13], -1
	s_cbranch_vccnz .LBB0_1151
	v_lshl_add_u32 v24, s14, 3, v32
	s_mov_b64 s[12:13], 0
